# v12 + sequence-DFT stage A: the 32 strided bf16 loads per item issued in two groups of 16 with counted waits instead of one load-wait round trip each
# speedup vs baseline: 1.0216x; 1.0107x over previous
; __device__ __forceinline__ float bf2f(unsigned short b) { return __uint_as_float((unsigned)b << 16); }
; __device__ __forceinline__ void fourier_stage_a(const Params& p, const Ctx& c, int l) {
;     ...
;   for (long i = c.gtid; i < (long)NB * 512 * 256; i += c.nthr) { const int t2 = (int)(i & 255), ch = (int)((i >> 8) & 511), b = (int)(i >> 17);
;     const bf16_t* Pb = PT + ((size_t)(0 * NB + b) * 512 + ch) * 4096 + t2; const bf16_t* Qb = PT + ((size_t)(1 * NB + b) * 512 + ch) * 4096 + t2;
;     float zr[16], zq[16];
; #pragma unroll
;     for (int t1 = 0; t1 < 16; ++t1) { zr[t1] = bf2f(Pb[256 * t1]); zq[t1] = bf2f(Qb[256 * t1]); }
;     bf16_t* Yo = Y + ((size_t)(b * 16) * 512 + ch) * 512 + t2;
; #pragma unroll
;     for (int k1 = 0; k1 < 16; ++k1) { float ar = 0.f, ai = 0.f;
; #pragma unroll
;       for (int t1 = 0; t1 < 16; ++t1) { const float cc = C16[(k1 * t1) & 15], ss = S16[(k1 * t1) & 15]; ar += zr[t1] * cc - zq[t1] * ss; ai -= zr[t1] * ss + zq[t1] * cc; }
.LBB0_506:
	v_alignbit_b32 v1, v11, v10, 17
	v_bfe_u32 v9, v10, 8, 9
	v_ashrrev_i64 v[12:13], 23, v[0:1]
	v_or_b32_e32 v12, v12, v9
	v_lshlrev_b64 v[12:13], 13, v[12:13]
	v_lshl_add_u64 v[12:13], v[6:7], 0, v[12:13]
	v_add_u32_e32 v15, 4, v1
	v_mov_b32_e32 v14, v0
	v_ashrrev_i64 v[14:15], 23, v[14:15]
	v_or_b32_e32 v14, v14, v9
	v_lshlrev_b64 v[14:15], 13, v[14:15]
	v_lshl_add_u64 v[14:15], v[6:7], 0, v[14:15]
	global_load_ushort v192, v[12:13], off
	global_load_ushort v193, v[14:15], off
	global_load_ushort v194, v[12:13], off offset:512
	global_load_ushort v195, v[14:15], off offset:512
	global_load_ushort v196, v[12:13], off offset:1024
	global_load_ushort v197, v[14:15], off offset:1024
	global_load_ushort v198, v[12:13], off offset:1536
	global_load_ushort v199, v[14:15], off offset:1536
	global_load_ushort v200, v[12:13], off offset:2048
	global_load_ushort v201, v[14:15], off offset:2048
	global_load_ushort v202, v[12:13], off offset:2560
	global_load_ushort v203, v[14:15], off offset:2560
	global_load_ushort v204, v[12:13], off offset:3072
	global_load_ushort v205, v[14:15], off offset:3072
	global_load_ushort v206, v[12:13], off offset:3584
	global_load_ushort v207, v[14:15], off offset:3584
	s_mov_b32 s0, 0x80000
	v_lshl_add_u64 v[10:11], v[10:11], 0, s[22:23]
	s_waitcnt vmcnt(15)
	v_lshlrev_b32_e32 v59, 16, v192
	s_waitcnt vmcnt(14)
	v_lshlrev_b32_e32 v54, 16, v193
	s_waitcnt vmcnt(13)
	v_lshlrev_b32_e32 v55, 16, v194
	s_waitcnt vmcnt(12)
	v_lshlrev_b32_e32 v114, 16, v195
	v_fmamk_f32 v123, v114, 0x80000000, v55
	v_fma_f32 v124, 0, v55, v114
	v_mul_f32_e32 v83, 0x3ec3ef15, v114
	v_mul_f32_e32 v66, 0x3f6c835e, v114
	s_waitcnt vmcnt(11)
	v_lshlrev_b32_e32 v122, 16, v196
	s_waitcnt vmcnt(10)
	v_lshlrev_b32_e32 v136, 16, v197
	v_fmamk_f32 v142, v136, 0x80000000, v122
	v_fma_f32 v65, 0, v122, v136
	v_mul_f32_e32 v67, 0x3f3504f3, v136
	v_fma_f32 v151, v122, s20, -v67
	v_fmamk_f32 v152, v122, 0x3f3504f3, v67
	v_fma_f32 v162, v122, 0, -v136
	v_fma_f32 v164, 0, v136, v122
	v_fma_f32 v174, v122, s92, -v67
	v_mul_f32_e32 v146, 0xbf3504f3, v136
	v_fmamk_f32 v175, v122, 0x3f3504f3, v146
	v_fma_f32 v186, v136, s83, -v122
	v_fma_f32 v136, v136, 0, -v122
	v_fmac_f32_e32 v67, 0xbf3504f3, v122
	s_waitcnt vmcnt(9)
	v_lshlrev_b32_e32 v53, 16, v198
	s_waitcnt vmcnt(8)
	v_lshlrev_b32_e32 v79, 16, v199
	v_fmamk_f32 v111, v79, 0x80000000, v53
	v_fma_f32 v116, 0, v53, v79
	v_mul_f32_e32 v147, 0x3f6c835e, v79
	v_mul_f32_e32 v68, 0x3ec3ef15, v79
	v_mul_f32_e32 v165, 0x3f3504f3, v79
	v_mul_f32_e32 v182, 0xbec3ef15, v79
	v_fma_f32 v140, v53, s20, -v165
	s_waitcnt vmcnt(7)
	v_lshlrev_b32_e32 v81, 16, v200
	s_waitcnt vmcnt(6)
	v_lshlrev_b32_e32 v94, 16, v201
	v_fmamk_f32 v105, v94, 0x80000000, v81
	v_fma_f32 v82, v81, 0, -v94
	v_fma_f32 v85, 0, v94, v81
	s_waitcnt vmcnt(5)
	v_lshlrev_b32_e32 v52, 16, v202
	s_waitcnt vmcnt(4)
	v_lshlrev_b32_e32 v112, 16, v203
	v_fmamk_f32 v107, v112, 0x80000000, v52
	v_fma_f32 v110, 0, v52, v112
	v_mul_f32_e32 v84, 0x3f6c835e, v112
	v_mul_f32_e32 v69, 0xbec3ef15, v112
	s_waitcnt vmcnt(3)
	v_lshlrev_b32_e32 v113, 16, v204
	s_waitcnt vmcnt(2)
	v_lshlrev_b32_e32 v131, 16, v205
	v_add_co_u32_e32 v12, vcc, s86, v12
	v_fmamk_f32 v143, v131, 0x80000000, v113
	s_nop 0
	v_addc_co_u32_e32 v13, vcc, 0, v13, vcc
	v_fma_f32 v127, 0, v113, v131
	v_mul_f32_e32 v86, 0x3f3504f3, v131
	v_fma_f32 v153, v113, s92, -v86
	v_mul_f32_e32 v70, 0xbf3504f3, v131
	v_fmamk_f32 v154, v113, 0x3f3504f3, v70
	v_fma_f32 v168, v131, 0, -v113
	v_fma_f32 v176, v113, s20, -v86
	v_fmamk_f32 v177, v113, 0x3f3504f3, v86
	v_fma_f32 v161, v131, s83, -v113
	v_fma_f32 v135, v113, s20, -v70
	v_fmac_f32_e32 v86, 0xbf3504f3, v113
	s_waitcnt vmcnt(1)
	v_lshlrev_b32_e32 v51, 16, v206
	v_add_co_u32_e32 v14, vcc, s86, v14
	s_waitcnt vmcnt(0)
	v_lshlrev_b32_e32 v74, 16, v207
	v_addc_co_u32_e32 v15, vcc, 0, v15, vcc
	global_load_ushort v192, v[12:13], off
	global_load_ushort v193, v[14:15], off
	global_load_ushort v194, v[12:13], off offset:512
	global_load_ushort v195, v[14:15], off offset:512
	global_load_ushort v196, v[12:13], off offset:1024
	global_load_ushort v197, v[14:15], off offset:1024
	global_load_ushort v198, v[12:13], off offset:1536
	global_load_ushort v199, v[14:15], off offset:1536
	global_load_ushort v200, v[12:13], off offset:2048
	global_load_ushort v201, v[14:15], off offset:2048
	global_load_ushort v202, v[12:13], off offset:2560
	global_load_ushort v203, v[14:15], off offset:2560
	global_load_ushort v204, v[12:13], off offset:3072
	global_load_ushort v205, v[12:13], off offset:3584
	global_load_ushort v206, v[14:15], off offset:3072
	global_load_ushort v207, v[14:15], off offset:3584
	v_fma_f32 v118, 0, v51, v74
	v_mul_f32_e32 v148, 0x3ec3ef15, v74
	v_mul_f32_e32 v71, 0xbf6c835e, v74
	v_mul_f32_e32 v169, 0xbf3504f3, v74
	v_mul_f32_e32 v183, 0x3f6c835e, v74
	s_waitcnt vmcnt(15)
	v_lshlrev_b32_e32 v56, 16, v192
	s_waitcnt vmcnt(14)
	v_lshlrev_b32_e32 v57, 16, v193
	v_fmamk_f32 v62, v57, 0x80000000, v56
	v_fma_f32 v63, 0, v56, v57
	v_fma_f32 v72, v57, s83, -v56
	v_fma_f32 v73, v56, 0, -v57
	s_waitcnt vmcnt(13)
	v_lshlrev_b32_e32 v50, 16, v194
	s_waitcnt vmcnt(12)
	v_lshlrev_b32_e32 v75, 16, v195
	v_fma_f32 v106, 0, v50, v75
	v_mul_f32_e32 v87, 0xbec3ef15, v75
	v_mul_f32_e32 v56, 0xbf6c835e, v75
	v_fma_f32 v187, v50, 0, -v75
	s_waitcnt vmcnt(11)
	v_lshlrev_b32_e32 v119, 16, v196
	s_waitcnt vmcnt(10)
	v_lshlrev_b32_e32 v133, 16, v197
	v_fmamk_f32 v144, v133, 0x80000000, v119
	v_fma_f32 v64, 0, v119, v133
	v_mul_f32_e32 v57, 0xbf3504f3, v133
	v_fma_f32 v155, v119, s92, -v57
	v_fmamk_f32 v156, v119, 0xbf3504f3, v57
	v_fma_f32 v121, v119, 0, -v133
	v_fma_f32 v171, 0, v133, v119
	v_mul_f32_e32 v189, 0x3f3504f3, v133
	v_fma_f32 v178, v119, s20, -v57
	v_fmamk_f32 v179, v119, 0xbf3504f3, v189
	v_fma_f32 v157, v133, s83, -v119
	v_fmac_f32_e32 v57, 0x3f3504f3, v119
	s_waitcnt vmcnt(9)
; __device__ __forceinline__ unsigned cvtpk(float lo, float hi) { unsigned r; asm volatile("v_cvt_pk_bf16_f32 %0, %1, %2" : "=v"(r) : "v"(lo), "v"(hi)); return r; }
; __device__ __forceinline__ float bf2f(unsigned short b) { return __uint_as_float((unsigned)b << 16); }
; __device__ __forceinline__ void fourier_stage_a(const Params& p, const Ctx& c, int l) {
;     ...
;     for (int t1 = 0; t1 < 16; ++t1) { zr[t1] = bf2f(Pb[256 * t1]); zq[t1] = bf2f(Qb[256 * t1]); }
;     bf16_t* Yo = Y + ((size_t)(b * 16) * 512 + ch) * 512 + t2;
; #pragma unroll
;     for (int k1 = 0; k1 < 16; ++k1) { float ar = 0.f, ai = 0.f;
; #pragma unroll
;       for (int t1 = 0; t1 < 16; ++t1) { const float cc = C16[(k1 * t1) & 15], ss = S16[(k1 * t1) & 15]; ar += zr[t1] * cc - zq[t1] * ss; ai -= zr[t1] * ss + zq[t1] * cc; }
;       const float ph = (float)(k1 * t2) * (1.f / 4096.f), ct = __builtin_amdgcn_cosf(ph), st = __builtin_amdgcn_sinf(ph);
;       const float yr = (ar * ct + ai * st) * 0.25f, yi = (ai * ct - ar * st) * 0.25f;
;       bf16_t* yo = Yo + (size_t)k1 * 512 * 512; const unsigned w = cvtpk(yr, yi); yo[0] = (bf16_t)(w & 0xffff); yo[256] = (bf16_t)(w >> 16); } }
	v_lshlrev_b32_e32 v48, 16, v198
	s_waitcnt vmcnt(8)
	v_lshlrev_b32_e32 v76, 16, v199
	v_fma_f32 v115, 0, v48, v76
	v_mul_f32_e32 v149, 0xbf6c835e, v76
	v_mul_f32_e32 v170, 0x3f3504f3, v76
	v_mul_f32_e32 v184, 0x3ec3ef15, v76
	v_fma_f32 v137, v48, s72, -v184
	s_waitcnt vmcnt(7)
	v_lshlrev_b32_e32 v49, 16, v200
	s_waitcnt vmcnt(6)
	v_lshlrev_b32_e32 v61, 16, v201
	v_fmamk_f32 v108, v61, 0x80000000, v49
	v_fma_f32 v80, 0, v49, v61
	v_fma_f32 v89, v61, 0, -v49
	s_waitcnt vmcnt(5)
	v_lshlrev_b32_e32 v47, 16, v202
	s_waitcnt vmcnt(4)
	v_lshlrev_b32_e32 v77, 16, v203
	v_fma_f32 v109, 0, v47, v77
	v_mul_f32_e32 v88, 0xbf6c835e, v77
	v_fma_f32 v188, v47, 0, -v77
	s_waitcnt vmcnt(3)
	v_lshlrev_b32_e32 v120, 16, v204
	s_waitcnt vmcnt(1)
	v_lshlrev_b32_e32 v134, 16, v206
	s_waitcnt vmcnt(2)
	v_lshlrev_b32_e32 v46, 16, v205
	v_lshlrev_b32_e32 v14, 10, v9
	v_mov_b32_e32 v15, v0
	v_mov_b32_e32 v9, v0
	v_fmamk_f32 v145, v134, 0x80000000, v120
	v_fma_f32 v132, 0, v120, v134
	v_mul_f32_e32 v90, 0xbf3504f3, v134
	v_fma_f32 v159, v120, s20, -v90
	v_fma_f32 v173, v134, 0, -v120
	v_fma_f32 v180, v120, s92, -v90
	v_fmamk_f32 v181, v120, 0xbf3504f3, v90
	v_fma_f32 v158, v134, s83, -v120
	v_fmac_f32_e32 v90, 0x3f3504f3, v120
	s_waitcnt vmcnt(0)
	v_lshlrev_b32_e32 v78, 16, v207
	v_lshlrev_b32_e32 v12, 4, v1
	v_ashrrev_i32_e32 v13, 31, v12
	v_lshlrev_b64 v[12:13], 19, v[12:13]
	v_lshl_add_u64 v[12:13], s[6:7], 0, v[12:13]
	v_fmamk_f32 v1, v54, 0x80000000, v59
	v_lshl_add_u64 v[12:13], v[12:13], 0, v[14:15]
	v_add_f32_e32 v58, 0, v1
	v_fmac_f32_e32 v54, 0, v59
	v_lshl_add_u64 v[12:13], v[12:13], 0, v[8:9]
	v_add_f32_e32 v1, v58, v123
	v_sub_f32_e64 v9, -v54, v124
	v_add_f32_e32 v1, v1, v142
	v_sub_f32_e32 v9, v9, v65
	v_add_f32_e32 v1, v1, v111
	v_sub_f32_e32 v9, v9, v116
	v_fma_f32 v59, 0, v81, v94
	v_add_f32_e32 v1, v1, v105
	v_sub_f32_e32 v9, v9, v59
	v_add_f32_e32 v1, v1, v107
	v_sub_f32_e32 v9, v9, v110
	v_add_f32_e32 v1, v1, v143
	v_sub_f32_e32 v9, v9, v127
	v_fmamk_f32 v14, v74, 0x80000000, v51
	v_add_f32_e32 v1, v1, v14
	v_sub_f32_e32 v9, v9, v118
	v_add_f32_e32 v1, v1, v62
	v_sub_f32_e32 v9, v9, v63
	v_fmamk_f32 v14, v75, 0x80000000, v50
	v_add_f32_e32 v1, v1, v14
	v_sub_f32_e32 v9, v9, v106
	v_add_f32_e32 v1, v1, v144
	v_sub_f32_e32 v9, v9, v64
	v_fmamk_f32 v14, v76, 0x80000000, v48
	v_add_f32_e32 v1, v1, v14
	v_sub_f32_e32 v9, v9, v115
	v_add_f32_e32 v1, v1, v108
	v_sub_f32_e32 v9, v9, v80
	v_fmamk_f32 v14, v77, 0x80000000, v47
	v_add_f32_e32 v1, v1, v14
	v_sub_f32_e32 v9, v9, v109
	v_add_f32_e32 v1, v1, v145
	v_sub_f32_e32 v9, v9, v132
	v_fmamk_f32 v14, v78, 0x80000000, v46
	v_fma_f32 v117, 0, v46, v78
	v_add_f32_e32 v1, v1, v14
	v_sub_f32_e32 v9, v9, v117
	v_fma_f32 v14, 0, v9, v1
	v_fmac_f32_e32 v9, 0x80000000, v1
	v_mul_f32_e32 v1, 0x3e800000, v9
	v_mul_f32_e32 v14, 0x3e800000, v14
	v_cvt_pk_bf16_f32 v1, v14, v1
	global_store_short v[12:13], v1, off
	global_store_short_d16_hi v[12:13], v1, off offset:512
	v_fma_f32 v1, v55, s78, -v83
	v_add_f32_e32 v1, v58, v1
	v_fmamk_f32 v9, v55, 0x3ec3ef15, v66
	v_sub_f32_e64 v9, -v54, v9
	v_add_f32_e32 v1, v1, v151
	v_fma_f32 v14, v53, s73, -v147
	v_sub_f32_e32 v9, v9, v152
	v_add_f32_e32 v1, v1, v14
	v_fmamk_f32 v14, v53, 0x3f6c835e, v68
	v_sub_f32_e32 v9, v9, v14
	v_add_f32_e32 v1, v1, v82
	v_fma_f32 v14, v52, s79, -v84
	v_sub_f32_e32 v9, v9, v85
	v_add_f32_e32 v1, v1, v14
	v_fmamk_f32 v14, v52, 0x3f6c835e, v69
	v_sub_f32_e32 v9, v9, v14
	v_add_f32_e32 v1, v1, v153
	v_fma_f32 v14, v51, s72, -v148
	v_sub_f32_e32 v9, v9, v154
	v_add_f32_e32 v1, v1, v14
	v_fmamk_f32 v14, v51, 0x3ec3ef15, v71
	v_sub_f32_e32 v9, v9, v14
	v_add_f32_e32 v1, v1, v72
	v_fma_f32 v14, v50, s72, -v87
	v_sub_f32_e32 v9, v9, v73
	v_add_f32_e32 v1, v1, v14
	v_fmamk_f32 v14, v50, 0xbec3ef15, v56
	v_sub_f32_e32 v9, v9, v14
	v_add_f32_e32 v1, v1, v155
	v_fma_f32 v14, v48, s79, -v149
	v_mul_f32_e32 v15, 0xbec3ef15, v76
	v_sub_f32_e32 v9, v9, v156
	v_add_f32_e32 v1, v1, v14
	v_fmamk_f32 v14, v48, 0xbf6c835e, v15
	v_sub_f32_e32 v9, v9, v14
	v_add_f32_e32 v1, v1, v80
	v_sub_f32_e32 v14, v9, v89
	v_fma_f32 v9, v47, s73, -v88
	v_add_f32_e32 v1, v1, v9
	v_mul_f32_e32 v9, 0x3ec3ef15, v77
	v_fmamk_f32 v60, v47, 0xbf6c835e, v9
	v_mul_f32_e32 v150, 0xbec3ef15, v78
	v_sub_f32_e32 v60, v14, v60
	v_add_f32_e32 v1, v1, v159
	v_mul_f32_e32 v14, 0x3f3504f3, v134
	v_fma_f32 v91, v46, s78, -v150
	v_fmamk_f32 v160, v120, 0xbf3504f3, v14
	v_add_f32_e32 v91, v1, v91
	v_mul_f32_e32 v1, 0x3f6c835e, v78
	v_sub_f32_e32 v60, v60, v160
	v_fmamk_f32 v92, v46, 0xbec3ef15, v1
	v_sub_f32_e32 v60, v60, v92
	v_mul_f32_e32 v92, v16, v91
	v_mul_f32_e32 v91, v17, v91
	v_fmac_f32_e32 v92, v17, v60
	v_fma_f32 v60, v16, v60, -v91
	v_mul_f32_e32 v92, 0x3e800000, v92
	v_mul_f32_e32 v60, 0x3e800000, v60
	v_cvt_pk_bf16_f32 v60, v92, v60
	v_add_co_u32_e32 v92, vcc, s0, v12
	v_mul_f32_e32 v91, 0x3f3504f3, v114
	s_nop 0
	v_addc_co_u32_e32 v93, vcc, 0, v13, vcc
	global_store_short v[92:93], v60, off
	global_store_short_d16_hi v[92:93], v60, off offset:512
	v_fma_f32 v60, v55, s20, -v91
	v_add_f32_e32 v60, v58, v60
	v_fmamk_f32 v92, v55, 0x3f3504f3, v91
	v_add_f32_e32 v60, v60, v162
	v_fma_f32 v93, v53, s92, -v165
	v_sub_f32_e64 v92, -v54, v92
	v_add_f32_e32 v60, v60, v93
	v_mul_f32_e32 v93, 0xbf3504f3, v79
	v_sub_f32_e32 v92, v92, v164
	v_fmamk_f32 v95, v53, 0x3f3504f3, v93
	v_sub_f32_e32 v92, v92, v95
	v_fma_f32 v95, v94, s83, -v81
	v_sub_f32_e32 v96, v92, v82
	v_mul_f32_e32 v92, 0xbf3504f3, v112
	v_add_f32_e32 v60, v60, v95
	v_fma_f32 v97, v52, s92, -v92
	v_add_f32_e32 v60, v60, v97
	v_fmamk_f32 v97, v52, 0xbf3504f3, v92
	v_sub_f32_e32 v96, v96, v97
	v_add_f32_e32 v60, v60, v127
; __device__ __forceinline__ unsigned cvtpk(float lo, float hi) { unsigned r; asm volatile("v_cvt_pk_bf16_f32 %0, %1, %2" : "=v"(r) : "v"(lo), "v"(hi)); return r; }
; __device__ __forceinline__ void fourier_stage_a(const Params& p, const Ctx& c, int l) {
;     ...
;     for (int k1 = 0; k1 < 16; ++k1) { float ar = 0.f, ai = 0.f;
; #pragma unroll
;       for (int t1 = 0; t1 < 16; ++t1) { const float cc = C16[(k1 * t1) & 15], ss = S16[(k1 * t1) & 15]; ar += zr[t1] * cc - zq[t1] * ss; ai -= zr[t1] * ss + zq[t1] * cc; }
;       const float ph = (float)(k1 * t2) * (1.f / 4096.f), ct = __builtin_amdgcn_cosf(ph), st = __builtin_amdgcn_sinf(ph);
;       const float yr = (ar * ct + ai * st) * 0.25f, yi = (ai * ct - ar * st) * 0.25f;
;       bf16_t* yo = Yo + (size_t)k1 * 512 * 512; const unsigned w = cvtpk(yr, yi); yo[0] = (bf16_t)(w & 0xffff); yo[256] = (bf16_t)(w >> 16); } }
	v_fma_f32 v97, v51, s20, -v169
	v_add_f32_e32 v60, v60, v97
	v_mul_f32_e32 v97, 0x3f3504f3, v74
	v_sub_f32_e32 v96, v96, v168
	v_fmamk_f32 v98, v51, 0xbf3504f3, v97
	v_sub_f32_e32 v96, v96, v98
	v_sub_f32_e32 v98, v96, v63
	v_mul_f32_e32 v96, 0x3f3504f3, v75
	v_add_f32_e32 v60, v60, v62
	v_fma_f32 v99, v50, s20, -v96
	v_add_f32_e32 v60, v60, v99
	v_fmamk_f32 v99, v50, 0x3f3504f3, v96
	v_sub_f32_e32 v98, v98, v99
	v_add_f32_e32 v60, v60, v121
	v_sub_f32_e32 v99, v98, v171
	v_fma_f32 v98, v48, s92, -v170
	v_add_f32_e32 v60, v60, v98
	v_mul_f32_e32 v98, 0xbf3504f3, v76
	v_fmamk_f32 v100, v48, 0x3f3504f3, v98
	v_sub_f32_e32 v99, v99, v100
	v_fma_f32 v100, v61, s83, -v49
	v_add_f32_e32 v101, v60, v100
	v_fma_f32 v60, v49, 0, -v61
	v_sub_f32_e32 v102, v99, v60
	v_mul_f32_e32 v99, 0xbf3504f3, v77
	v_fma_f32 v103, v47, s92, -v99
	v_add_f32_e32 v101, v101, v103
	v_fmamk_f32 v103, v47, 0xbf3504f3, v99
	v_mul_f32_e32 v172, 0xbf3504f3, v78
	v_sub_f32_e32 v102, v102, v103
	v_add_f32_e32 v101, v101, v132
	v_fma_f32 v103, v46, s20, -v172
	v_add_f32_e32 v103, v101, v103
	v_mul_f32_e32 v101, 0x3f3504f3, v78
	v_sub_f32_e32 v102, v102, v173
	v_fmamk_f32 v104, v46, 0xbf3504f3, v101
	v_sub_f32_e32 v102, v102, v104
	v_mul_f32_e32 v104, v18, v103
	v_mul_f32_e32 v103, v19, v103
	v_fmac_f32_e32 v104, v19, v102
	v_fma_f32 v102, v18, v102, -v103
	v_mul_f32_e32 v104, 0x3e800000, v104
	v_mul_f32_e32 v102, 0x3e800000, v102
	s_mov_b32 s0, 0x100000
	v_cvt_pk_bf16_f32 v104, v104, v102
	v_add_co_u32_e32 v102, vcc, s0, v12
	v_fmac_f32_e32 v49, 0, v61
	s_nop 0
	v_addc_co_u32_e32 v103, vcc, 0, v13, vcc
	global_store_short v[102:103], v104, off
	global_store_short_d16_hi v[102:103], v104, off offset:512
	v_fma_f32 v102, v55, s73, -v66
	v_add_f32_e32 v102, v58, v102
	v_fmamk_f32 v103, v55, 0x3f6c835e, v83
	v_add_f32_e32 v102, v102, v174
	v_fma_f32 v104, v53, s72, -v182
	v_sub_f32_e64 v103, -v54, v103
	v_add_f32_e32 v104, v102, v104
	v_mul_f32_e32 v102, 0xbf6c835e, v79
	v_sub_f32_e32 v103, v103, v175
	v_fmamk_f32 v125, v53, 0xbec3ef15, v102
	v_sub_f32_e32 v125, v103, v125
	v_add_f32_e32 v104, v104, v59
	v_fma_f32 v103, v94, 0, -v81
	v_fma_f32 v94, v52, s78, -v69
	v_sub_f32_e32 v81, v125, v103
	v_add_f32_e32 v94, v104, v94
	v_fmamk_f32 v104, v52, 0xbec3ef15, v84
	v_sub_f32_e32 v81, v81, v104
	v_add_f32_e32 v94, v94, v176
	v_fma_f32 v104, v51, s79, -v183
	v_add_f32_e32 v94, v94, v104
	v_mul_f32_e32 v104, 0xbec3ef15, v74
	v_sub_f32_e32 v81, v81, v177
	v_fmamk_f32 v125, v51, 0x3f6c835e, v104
	v_sub_f32_e32 v81, v81, v125
	v_add_f32_e32 v94, v94, v72
	v_fma_f32 v125, v50, s79, -v56
	v_sub_f32_e32 v81, v81, v73
	v_add_f32_e32 v94, v94, v125
	v_fmamk_f32 v125, v50, 0xbf6c835e, v87
	v_sub_f32_e32 v81, v81, v125
	v_add_f32_e32 v94, v94, v178
	v_sub_f32_e32 v125, v81, v179
	v_fma_f32 v81, v48, s78, -v184
	v_add_f32_e32 v94, v94, v81
	v_mul_f32_e32 v81, 0x3f6c835e, v76
	v_fmamk_f32 v126, v48, 0x3ec3ef15, v81
	v_sub_f32_e32 v125, v125, v126
	v_add_f32_e32 v94, v94, v60
	v_sub_f32_e32 v61, v125, v49
	v_fma_f32 v125, v47, s72, -v9
	v_add_f32_e32 v94, v94, v125
	v_fmamk_f32 v125, v47, 0x3ec3ef15, v88
	v_sub_f32_e32 v61, v61, v125
	v_mul_f32_e32 v185, 0xbf6c835e, v78
	v_add_f32_e32 v94, v94, v180
	v_sub_f32_e32 v125, v61, v181
	v_fma_f32 v61, v46, s73, -v185
	v_add_f32_e32 v94, v94, v61
	v_mul_f32_e32 v61, 0x3ec3ef15, v78
	v_fmamk_f32 v126, v46, 0xbf6c835e, v61
	v_sub_f32_e32 v125, v125, v126
	v_mul_f32_e32 v126, v20, v94
	v_mul_f32_e32 v94, v21, v94
	v_fma_f32 v94, v20, v125, -v94
	s_mov_b32 s0, 0x180000
	v_fmac_f32_e32 v126, v21, v125
	v_mul_f32_e32 v94, 0x3e800000, v94
	v_add_co_u32_e32 v128, vcc, s0, v12
	v_mul_f32_e32 v126, 0x3e800000, v126
	v_cvt_pk_bf16_f32 v94, v126, v94
	s_nop 0
	v_addc_co_u32_e32 v129, vcc, 0, v13, vcc
	global_store_short v[128:129], v94, off
	global_store_short_d16_hi v[128:129], v94, off offset:512
	v_fma_f32 v94, v55, 0, -v114
	v_add_f32_e32 v94, v58, v94
	v_fma_f32 v125, 0, v114, v55
	v_sub_f32_e64 v125, -v54, v125
	v_add_f32_e32 v94, v94, v186
	v_sub_f32_e32 v125, v125, v162
	v_add_f32_e32 v94, v94, v116
	v_add_f32_e32 v111, v125, v111
	v_add_f32_e32 v94, v94, v105
	v_fma_f32 v116, v52, 0, -v112
	v_sub_f32_e32 v111, v111, v59
	v_add_f32_e32 v94, v94, v116
	v_fma_f32 v116, 0, v112, v52
	v_sub_f32_e32 v111, v111, v116
	v_add_f32_e32 v94, v94, v161
	v_fma_f32 v116, v113, 0, -v131
	v_sub_f32_e32 v111, v111, v116
	v_add_f32_e32 v94, v94, v118
	v_fma_f32 v118, v74, 0, -v51
	v_sub_f32_e32 v111, v111, v118
	v_add_f32_e32 v94, v94, v62
	v_sub_f32_e32 v111, v111, v63
	v_add_f32_e32 v94, v94, v187
	v_fma_f32 v118, 0, v75, v50
	v_sub_f32_e32 v111, v111, v118
	v_add_f32_e32 v94, v94, v157
	v_sub_f32_e32 v111, v111, v121
	v_add_f32_e32 v94, v94, v115
	v_fma_f32 v115, v76, 0, -v48
	v_sub_f32_e32 v111, v111, v115
	v_add_f32_e32 v94, v94, v108
	v_sub_f32_e32 v111, v111, v80
	v_add_f32_e32 v94, v94, v188
	v_fma_f32 v115, 0, v77, v47
	v_sub_f32_e32 v111, v111, v115
	v_add_f32_e32 v94, v94, v158
	v_fma_f32 v115, v120, 0, -v134
	v_sub_f32_e32 v111, v111, v115
	v_add_f32_e32 v94, v94, v117
	v_fma_f32 v117, v78, 0, -v46
	v_sub_f32_e32 v111, v111, v117
	v_mul_f32_e32 v117, v23, v111
	v_fmac_f32_e32 v117, v22, v94
	v_mul_f32_e32 v94, v23, v94
	v_fma_f32 v94, v22, v111, -v94
	s_mov_b32 s0, 0x200000
	v_mul_f32_e32 v94, 0x3e800000, v94
	v_add_co_u32_e32 v128, vcc, s0, v12
	v_mul_f32_e32 v117, 0x3e800000, v117
	v_cvt_pk_bf16_f32 v94, v117, v94
	s_nop 0
	v_addc_co_u32_e32 v129, vcc, 0, v13, vcc
	global_store_short v[128:129], v94, off
	global_store_short_d16_hi v[128:129], v94, off offset:512
	v_fma_f32 v94, v55, s79, -v66
	v_mul_f32_e32 v117, 0xbec3ef15, v114
	v_add_f32_e32 v94, v58, v94
; __device__ __forceinline__ unsigned cvtpk(float lo, float hi) { unsigned r; asm volatile("v_cvt_pk_bf16_f32 %0, %1, %2" : "=v"(r) : "v"(lo), "v"(hi)); return r; }
; __device__ __forceinline__ void fourier_stage_a(const Params& p, const Ctx& c, int l) {
;     ...
;     for (int k1 = 0; k1 < 16; ++k1) { float ar = 0.f, ai = 0.f;
; #pragma unroll
;       for (int t1 = 0; t1 < 16; ++t1) { const float cc = C16[(k1 * t1) & 15], ss = S16[(k1 * t1) & 15]; ar += zr[t1] * cc - zq[t1] * ss; ai -= zr[t1] * ss + zq[t1] * cc; }
;       const float ph = (float)(k1 * t2) * (1.f / 4096.f), ct = __builtin_amdgcn_cosf(ph), st = __builtin_amdgcn_sinf(ph);
;       const float yr = (ar * ct + ai * st) * 0.25f, yi = (ai * ct - ar * st) * 0.25f;
;       bf16_t* yo = Yo + (size_t)k1 * 512 * 512; const unsigned w = cvtpk(yr, yi); yo[0] = (bf16_t)(w & 0xffff); yo[256] = (bf16_t)(w >> 16); } }
	v_fmamk_f32 v111, v55, 0x3f6c835e, v117
	v_fma_f32 v125, v122, s92, -v146
	v_sub_f32_e64 v111, -v54, v111
	v_add_f32_e32 v94, v94, v125
	v_fmamk_f32 v126, v122, 0xbf3504f3, v146
	v_fma_f32 v118, v53, s78, -v182
	v_sub_f32_e32 v111, v111, v126
	v_add_f32_e32 v94, v94, v118
	v_fmamk_f32 v118, v53, 0xbec3ef15, v147
	v_sub_f32_e32 v111, v111, v118
	v_add_f32_e32 v94, v94, v82
	v_fma_f32 v118, v52, s72, -v69
	v_add_f32_e32 v94, v94, v118
	v_mul_f32_e32 v118, 0xbf6c835e, v112
	v_sub_f32_e32 v111, v111, v85
	v_fmamk_f32 v128, v52, 0xbec3ef15, v118
	v_sub_f32_e32 v111, v111, v128
	v_add_f32_e32 v94, v94, v135
	v_fma_f32 v128, v51, s73, -v183
	v_sub_f32_e32 v111, v111, v86
	v_add_f32_e32 v94, v94, v128
	v_fmamk_f32 v128, v51, 0x3f6c835e, v148
	v_sub_f32_e32 v111, v111, v128
	v_add_f32_e32 v94, v94, v72
	v_sub_f32_e32 v128, v111, v73
	v_fma_f32 v111, v50, s73, -v56
	v_add_f32_e32 v94, v94, v111
	v_mul_f32_e32 v111, 0x3ec3ef15, v75
	v_fmamk_f32 v129, v50, 0xbf6c835e, v111
	v_sub_f32_e32 v130, v128, v129
	v_fma_f32 v128, v119, s20, -v189
	v_add_f32_e32 v94, v94, v128
	v_fmamk_f32 v129, v119, 0x3f3504f3, v189
	v_sub_f32_e32 v130, v130, v129
	v_add_f32_e32 v94, v94, v137
	v_fmamk_f32 v137, v48, 0x3ec3ef15, v149
	v_sub_f32_e32 v130, v130, v137
	v_add_f32_e32 v94, v94, v80
	v_fma_f32 v137, v47, s78, -v9
	v_add_f32_e32 v137, v94, v137
	v_mul_f32_e32 v94, 0x3f6c835e, v77
	v_sub_f32_e32 v130, v130, v89
	v_fmamk_f32 v138, v47, 0x3ec3ef15, v94
	v_sub_f32_e32 v138, v130, v138
	v_fma_f32 v130, v120, s92, -v14
	v_add_f32_e32 v137, v137, v130
	v_fma_f32 v139, v46, s79, -v185
	v_sub_f32_e32 v138, v138, v90
	v_add_f32_e32 v137, v137, v139
	v_fmamk_f32 v139, v46, 0xbf6c835e, v150
	v_sub_f32_e32 v138, v138, v139
	v_mul_f32_e32 v139, v24, v137
	v_mul_f32_e32 v137, v25, v137
	v_fmac_f32_e32 v139, v25, v138
	v_fma_f32 v137, v24, v138, -v137
	s_mov_b32 s0, 0x280000
	v_mul_f32_e32 v139, 0x3e800000, v139
	v_mul_f32_e32 v137, 0x3e800000, v137
	v_add_co_u32_e32 v138, vcc, s0, v12
	v_cvt_pk_bf16_f32 v137, v139, v137
	s_mov_b32 s0, 0x300000
	s_nop 0
	v_addc_co_u32_e32 v139, vcc, 0, v13, vcc
	global_store_short v[138:139], v137, off
	global_store_short_d16_hi v[138:139], v137, off offset:512
	v_fma_f32 v137, v55, s92, -v91
	v_add_f32_e32 v138, v58, v137
	v_mul_f32_e32 v137, 0xbf3504f3, v114
	v_fmamk_f32 v139, v55, 0x3f3504f3, v137
	v_sub_f32_e64 v139, -v54, v139
	v_add_f32_e32 v138, v138, v65
	v_sub_f32_e32 v139, v139, v136
	v_add_f32_e32 v138, v138, v140
	v_fmamk_f32 v140, v53, 0x3f3504f3, v165
	v_sub_f32_e32 v139, v139, v140
	v_add_f32_e32 v138, v138, v95
	v_fma_f32 v140, v52, s20, -v92
	v_add_f32_e32 v138, v138, v140
	v_mul_f32_e32 v140, 0x3f3504f3, v112
	v_sub_f32_e32 v139, v139, v82
	v_fmamk_f32 v141, v52, 0xbf3504f3, v140
	v_sub_f32_e32 v139, v139, v141
	v_fma_f32 v141, 0, v131, v113
	v_add_f32_e32 v138, v138, v116
	v_sub_f32_e32 v131, v139, v141
	v_fma_f32 v139, v51, s92, -v169
	v_add_f32_e32 v138, v138, v139
	v_fmamk_f32 v139, v51, 0xbf3504f3, v169
	v_sub_f32_e32 v131, v131, v139
	v_add_f32_e32 v138, v138, v62
	v_fma_f32 v139, v50, s92, -v96
	v_add_f32_e32 v139, v138, v139
	v_mul_f32_e32 v138, 0xbf3504f3, v75
	v_sub_f32_e32 v131, v131, v63
	v_fmamk_f32 v163, v50, 0x3f3504f3, v138
	v_sub_f32_e32 v163, v131, v163
	v_fma_f32 v131, v133, 0, -v119
	v_add_f32_e32 v139, v139, v64
	v_sub_f32_e32 v133, v163, v131
	v_fma_f32 v163, v48, s20, -v170
	v_add_f32_e32 v139, v139, v163
	v_fmamk_f32 v163, v48, 0x3f3504f3, v170
	v_sub_f32_e32 v133, v133, v163
	v_add_f32_e32 v139, v139, v100
	v_fma_f32 v163, v47, s20, -v99
	v_add_f32_e32 v163, v139, v163
	v_mul_f32_e32 v139, 0x3f3504f3, v77
	v_sub_f32_e32 v133, v133, v60
	v_fmamk_f32 v166, v47, 0xbf3504f3, v139
	v_sub_f32_e32 v166, v133, v166
	v_fma_f32 v133, 0, v134, v120
	v_add_f32_e32 v163, v163, v115
	v_sub_f32_e32 v134, v166, v133
	v_fma_f32 v166, v46, s92, -v172
	v_add_f32_e32 v163, v163, v166
	v_fmamk_f32 v166, v46, 0xbf3504f3, v172
	v_sub_f32_e32 v134, v134, v166
	v_mul_f32_e32 v166, v26, v163
	v_mul_f32_e32 v163, v27, v163
	v_fmac_f32_e32 v166, v27, v134
	v_fma_f32 v134, v26, v134, -v163
	v_mul_f32_e32 v166, 0x3e800000, v166
	v_mul_f32_e32 v134, 0x3e800000, v134
	v_cvt_pk_bf16_f32 v134, v166, v134
	v_add_co_u32_e32 v166, vcc, s0, v12
	v_mul_f32_e32 v163, 0xbf6c835e, v114
	s_nop 0
	v_addc_co_u32_e32 v167, vcc, 0, v13, vcc
	global_store_short v[166:167], v134, off
	global_store_short_d16_hi v[166:167], v134, off offset:512
	v_fma_f32 v134, v55, s72, -v83
	v_add_f32_e32 v166, v58, v134
	v_fmamk_f32 v134, v55, 0x3ec3ef15, v163
	v_sub_f32_e64 v167, -v54, v134
	v_fma_f32 v134, v122, s20, -v146
	v_add_f32_e32 v146, v166, v134
	v_fma_f32 v166, v53, s79, -v147
	v_sub_f32_e32 v122, v167, v67
	v_add_f32_e32 v146, v146, v166
	v_fmamk_f32 v166, v53, 0x3f6c835e, v182
	v_sub_f32_e32 v122, v122, v166
	v_add_f32_e32 v146, v146, v59
	v_fma_f32 v166, v52, s73, -v84
	v_mul_f32_e32 v167, 0x3ec3ef15, v112
	v_sub_f32_e32 v122, v122, v103
	v_add_f32_e32 v166, v146, v166
	v_fmamk_f32 v146, v52, 0x3f6c835e, v167
	v_sub_f32_e32 v122, v122, v146
	v_fma_f32 v146, v113, s92, -v70
	v_fmac_f32_e32 v70, 0xbf3504f3, v113
	v_add_f32_e32 v166, v166, v146
	v_sub_f32_e32 v113, v122, v70
	v_fma_f32 v122, v51, s78, -v148
	v_add_f32_e32 v122, v166, v122
	v_fmamk_f32 v166, v51, 0x3ec3ef15, v183
	v_sub_f32_e32 v113, v113, v166
	v_add_f32_e32 v122, v122, v72
	v_fma_f32 v166, v50, s78, -v87
	v_add_f32_e32 v190, v122, v166
	v_mul_f32_e32 v166, 0x3f6c835e, v75
	v_sub_f32_e32 v113, v113, v73
	v_fmamk_f32 v122, v50, 0xbec3ef15, v166
	v_sub_f32_e32 v113, v113, v122
	v_fma_f32 v122, v119, s92, -v189
	v_add_f32_e32 v189, v190, v122
	v_fma_f32 v119, v48, s73, -v149
; __device__ __forceinline__ unsigned cvtpk(float lo, float hi) { unsigned r; asm volatile("v_cvt_pk_bf16_f32 %0, %1, %2" : "=v"(r) : "v"(lo), "v"(hi)); return r; }
; __device__ __forceinline__ void fourier_stage_a(const Params& p, const Ctx& c, int l) {
;     ...
;     for (int k1 = 0; k1 < 16; ++k1) { float ar = 0.f, ai = 0.f;
; #pragma unroll
;       for (int t1 = 0; t1 < 16; ++t1) { const float cc = C16[(k1 * t1) & 15], ss = S16[(k1 * t1) & 15]; ar += zr[t1] * cc - zq[t1] * ss; ai -= zr[t1] * ss + zq[t1] * cc; }
;       const float ph = (float)(k1 * t2) * (1.f / 4096.f), ct = __builtin_amdgcn_cosf(ph), st = __builtin_amdgcn_sinf(ph);
;       const float yr = (ar * ct + ai * st) * 0.25f, yi = (ai * ct - ar * st) * 0.25f;
;       bf16_t* yo = Yo + (size_t)k1 * 512 * 512; const unsigned w = cvtpk(yr, yi); yo[0] = (bf16_t)(w & 0xffff); yo[256] = (bf16_t)(w >> 16); } }
	v_sub_f32_e32 v113, v113, v57
	v_add_f32_e32 v119, v189, v119
	v_fmamk_f32 v189, v48, 0xbf6c835e, v184
	v_sub_f32_e32 v113, v113, v189
	v_add_f32_e32 v119, v119, v60
	v_fma_f32 v189, v47, s79, -v88
	v_add_f32_e32 v189, v119, v189
	v_mul_f32_e32 v119, 0xbec3ef15, v77
	v_sub_f32_e32 v113, v113, v49
	v_fmamk_f32 v190, v47, 0xbf6c835e, v119
	v_sub_f32_e32 v190, v113, v190
	v_fma_f32 v113, v120, s20, -v14
	v_fmac_f32_e32 v14, 0x3f3504f3, v120
	v_add_f32_e32 v189, v189, v113
	v_sub_f32_e32 v120, v190, v14
	v_fma_f32 v190, v46, s72, -v150
	v_add_f32_e32 v189, v189, v190
	v_fmamk_f32 v190, v46, 0xbec3ef15, v185
	v_sub_f32_e32 v120, v120, v190
	v_mul_f32_e32 v190, v28, v189
	v_mul_f32_e32 v189, v29, v189
	v_fmac_f32_e32 v190, v29, v120
	v_fma_f32 v120, v28, v120, -v189
	v_mul_f32_e32 v190, 0x3e800000, v190
	v_mul_f32_e32 v120, 0x3e800000, v120
	s_mov_b32 s0, 0x380000
	v_cvt_pk_bf16_f32 v120, v190, v120
	v_add_co_u32_e32 v190, vcc, s0, v12
	s_mov_b32 s0, 0x400000
	s_nop 0
	v_addc_co_u32_e32 v191, vcc, 0, v13, vcc
	global_store_short v[190:191], v120, off
	global_store_short_d16_hi v[190:191], v120, off offset:512
	v_fma_f32 v120, v114, s83, -v55
	v_add_f32_e32 v120, v58, v120
	v_fmac_f32_e32 v114, 0x80000000, v55
	v_add_f32_e64 v114, -v54, v114
	v_add_f32_e32 v120, v120, v142
	v_fma_f32 v142, v79, s83, -v53
	v_sub_f32_e32 v114, v114, v65
	v_add_f32_e32 v120, v120, v142
	v_fmamk_f32 v142, v53, 0x80000000, v79
	v_add_f32_e32 v114, v114, v142
	v_add_f32_e32 v120, v120, v105
	v_fma_f32 v142, v112, s83, -v52
	v_sub_f32_e32 v114, v114, v59
	v_add_f32_e32 v120, v120, v142
	v_fmac_f32_e32 v112, 0x80000000, v52
	v_add_f32_e32 v112, v114, v112
	v_add_f32_e32 v114, v120, v143
	v_fma_f32 v120, v74, s83, -v51
	v_sub_f32_e32 v112, v112, v127
	v_add_f32_e32 v114, v114, v120
	v_fma_f32 v120, v51, 0, -v74
	v_sub_f32_e32 v112, v112, v120
	v_add_f32_e32 v114, v114, v62
	v_sub_f32_e32 v112, v112, v63
	v_fma_f32 v142, v75, s83, -v50
	v_add_f32_e32 v114, v114, v142
	v_sub_f32_e32 v112, v112, v187
	v_add_f32_e32 v114, v114, v144
	v_sub_f32_e32 v142, v112, v64
	v_fma_f32 v112, v76, s83, -v48
	v_add_f32_e32 v114, v114, v112
	v_fma_f32 v112, v48, 0, -v76
	v_sub_f32_e32 v142, v142, v112
	v_add_f32_e32 v114, v114, v108
	v_fma_f32 v143, v77, s83, -v47
	v_sub_f32_e32 v142, v142, v80
	v_add_f32_e32 v114, v114, v143
	v_sub_f32_e32 v142, v142, v188
	v_add_f32_e32 v114, v114, v145
	v_fma_f32 v143, v78, s83, -v46
	v_sub_f32_e32 v142, v142, v132
	v_add_f32_e32 v143, v114, v143
	v_fma_f32 v114, v46, 0, -v78
	v_sub_f32_e32 v142, v142, v114
	v_mul_f32_e32 v144, v30, v143
	v_mul_f32_e32 v143, v31, v143
	v_fmac_f32_e32 v144, v31, v142
	v_fma_f32 v142, v30, v142, -v143
	v_mul_f32_e32 v144, 0x3e800000, v144
	v_mul_f32_e32 v142, 0x3e800000, v142
	v_cvt_pk_bf16_f32 v144, v144, v142
	v_add_co_u32_e32 v142, vcc, s0, v12
	v_fmac_f32_e32 v182, 0xbf6c835e, v53
	s_nop 0
	v_addc_co_u32_e32 v143, vcc, 0, v13, vcc
	global_store_short v[142:143], v144, off
	global_store_short_d16_hi v[142:143], v144, off offset:512
	v_fma_f32 v142, v55, s72, -v117
	v_add_f32_e32 v142, v58, v142
	v_fmamk_f32 v143, v55, 0xbec3ef15, v163
	v_sub_f32_e64 v143, -v54, v143
	v_add_f32_e32 v142, v142, v151
	v_fma_f32 v144, v53, s79, -v102
	v_sub_f32_e32 v143, v143, v152
	v_add_f32_e32 v142, v142, v144
	v_sub_f32_e32 v143, v143, v182
	v_add_f32_e32 v142, v142, v82
	v_fma_f32 v144, v52, s73, -v118
	v_sub_f32_e32 v143, v143, v85
	v_add_f32_e32 v142, v142, v144
	v_fmamk_f32 v144, v52, 0xbf6c835e, v167
	v_sub_f32_e32 v143, v143, v144
	v_add_f32_e32 v142, v142, v153
	v_fma_f32 v144, v51, s78, -v104
	v_sub_f32_e32 v143, v143, v154
	v_add_f32_e32 v142, v142, v144
	v_fmac_f32_e32 v183, 0xbec3ef15, v51
	v_sub_f32_e32 v143, v143, v183
	v_add_f32_e32 v142, v142, v72
	v_fma_f32 v144, v50, s78, -v111
	v_sub_f32_e32 v143, v143, v73
	v_add_f32_e32 v142, v142, v144
	v_fmamk_f32 v144, v50, 0x3ec3ef15, v166
	v_sub_f32_e32 v143, v143, v144
	v_add_f32_e32 v142, v142, v155
	v_fma_f32 v144, v48, s73, -v81
	v_sub_f32_e32 v143, v143, v156
	v_add_f32_e32 v142, v142, v144
	v_fmac_f32_e32 v184, 0x3f6c835e, v48
	v_sub_f32_e32 v143, v143, v184
	v_add_f32_e32 v142, v142, v80
	v_fma_f32 v144, v47, s79, -v94
	v_sub_f32_e32 v143, v143, v89
	v_add_f32_e32 v142, v142, v144
	v_fmamk_f32 v144, v47, 0x3f6c835e, v119
	v_sub_f32_e32 v143, v143, v144
	v_add_f32_e32 v142, v142, v159
	v_fma_f32 v144, v46, s72, -v61
	v_sub_f32_e32 v143, v143, v160
	v_add_f32_e32 v142, v142, v144
	v_fmac_f32_e32 v185, 0x3ec3ef15, v46
	v_sub_f32_e32 v143, v143, v185
	v_mul_f32_e32 v144, v32, v142
	v_mul_f32_e32 v142, v33, v142
	v_fmac_f32_e32 v144, v33, v143
	v_fma_f32 v142, v32, v143, -v142
	v_mul_f32_e32 v144, 0x3e800000, v144
	v_mul_f32_e32 v142, 0x3e800000, v142
	s_mov_b32 s0, 0x480000
	v_cvt_pk_bf16_f32 v144, v144, v142
	v_add_co_u32_e32 v142, vcc, s0, v12
	v_fmac_f32_e32 v165, 0xbf3504f3, v53
	s_nop 0
	v_addc_co_u32_e32 v143, vcc, 0, v13, vcc
	global_store_short v[142:143], v144, off
	global_store_short_d16_hi v[142:143], v144, off offset:512
	v_fma_f32 v142, v55, s92, -v137
	v_add_f32_e32 v142, v58, v142
	v_fmamk_f32 v143, v55, 0xbf3504f3, v137
	v_sub_f32_e64 v143, -v54, v143
	v_add_f32_e32 v142, v142, v162
	v_fma_f32 v144, v53, s20, -v93
	v_sub_f32_e32 v143, v143, v164
	v_add_f32_e32 v142, v142, v144
	v_sub_f32_e32 v143, v143, v165
	v_add_f32_e32 v142, v142, v95
	v_fma_f32 v144, v52, s20, -v140
	v_sub_f32_e32 v143, v143, v82
	v_add_f32_e32 v142, v142, v144
	v_fmamk_f32 v144, v52, 0x3f3504f3, v140
	v_sub_f32_e32 v143, v143, v144
	v_add_f32_e32 v127, v142, v127
	v_sub_f32_e32 v142, v143, v168
	v_fma_f32 v143, v51, s92, -v97
	v_add_f32_e32 v127, v127, v143
	v_fmac_f32_e32 v169, 0x3f3504f3, v51
; __device__ __forceinline__ unsigned cvtpk(float lo, float hi) { unsigned r; asm volatile("v_cvt_pk_bf16_f32 %0, %1, %2" : "=v"(r) : "v"(lo), "v"(hi)); return r; }
; __device__ __forceinline__ void fourier_stage_a(const Params& p, const Ctx& c, int l) {
;     ...
;     for (int k1 = 0; k1 < 16; ++k1) { float ar = 0.f, ai = 0.f;
; #pragma unroll
;       for (int t1 = 0; t1 < 16; ++t1) { const float cc = C16[(k1 * t1) & 15], ss = S16[(k1 * t1) & 15]; ar += zr[t1] * cc - zq[t1] * ss; ai -= zr[t1] * ss + zq[t1] * cc; }
;       const float ph = (float)(k1 * t2) * (1.f / 4096.f), ct = __builtin_amdgcn_cosf(ph), st = __builtin_amdgcn_sinf(ph);
;       const float yr = (ar * ct + ai * st) * 0.25f, yi = (ai * ct - ar * st) * 0.25f;
;       bf16_t* yo = Yo + (size_t)k1 * 512 * 512; const unsigned w = cvtpk(yr, yi); yo[0] = (bf16_t)(w & 0xffff); yo[256] = (bf16_t)(w >> 16); } }
	v_sub_f32_e32 v142, v142, v169
	v_add_f32_e32 v127, v127, v62
	v_fma_f32 v143, v50, s92, -v138
	v_sub_f32_e32 v142, v142, v63
	v_add_f32_e32 v127, v127, v143
	v_fmamk_f32 v143, v50, 0xbf3504f3, v138
	v_sub_f32_e32 v142, v142, v143
	v_add_f32_e32 v127, v127, v121
	v_fma_f32 v143, v48, s20, -v98
	v_sub_f32_e32 v142, v142, v171
	v_add_f32_e32 v127, v127, v143
	v_fmac_f32_e32 v170, 0xbf3504f3, v48
	v_sub_f32_e32 v142, v142, v170
	v_add_f32_e32 v127, v127, v100
	v_fma_f32 v143, v47, s20, -v139
	v_sub_f32_e32 v142, v142, v60
	v_add_f32_e32 v127, v127, v143
	v_fmamk_f32 v143, v47, 0x3f3504f3, v139
	v_sub_f32_e32 v142, v142, v143
	v_add_f32_e32 v127, v127, v132
	v_sub_f32_e32 v132, v142, v173
	v_fma_f32 v142, v46, s92, -v101
	v_add_f32_e32 v127, v127, v142
	v_fmac_f32_e32 v172, 0x3f3504f3, v46
	v_sub_f32_e32 v132, v132, v172
	v_mul_f32_e32 v142, v34, v127
	v_mul_f32_e32 v127, v35, v127
	v_fmac_f32_e32 v142, v35, v132
	v_fma_f32 v127, v34, v132, -v127
	v_mul_f32_e32 v142, 0x3e800000, v142
	v_mul_f32_e32 v127, 0x3e800000, v127
	s_mov_b32 s0, 0x500000
	v_cvt_pk_bf16_f32 v127, v142, v127
	v_add_co_u32_e32 v142, vcc, s0, v12
	v_fmamk_f32 v132, v55, 0xbf6c835e, v117
	s_nop 0
	v_addc_co_u32_e32 v143, vcc, 0, v13, vcc
	global_store_short v[142:143], v127, off
	global_store_short_d16_hi v[142:143], v127, off offset:512
	v_fma_f32 v127, v55, s79, -v163
	v_add_f32_e32 v127, v58, v127
	v_sub_f32_e64 v132, -v54, v132
	v_add_f32_e32 v127, v127, v174
	v_fma_f32 v142, v53, s78, -v68
	v_sub_f32_e32 v132, v132, v175
	v_add_f32_e32 v127, v127, v142
	v_fmac_f32_e32 v147, 0x3ec3ef15, v53
	v_sub_f32_e32 v132, v132, v147
	v_add_f32_e32 v127, v127, v59
	v_fma_f32 v142, v52, s72, -v167
	v_sub_f32_e32 v132, v132, v103
	v_add_f32_e32 v127, v127, v142
	v_fmamk_f32 v142, v52, 0x3ec3ef15, v118
	v_sub_f32_e32 v132, v132, v142
	v_add_f32_e32 v127, v127, v176
	v_fma_f32 v142, v51, s73, -v71
	v_sub_f32_e32 v132, v132, v177
	v_add_f32_e32 v127, v127, v142
	v_fmac_f32_e32 v148, 0xbf6c835e, v51
	v_sub_f32_e32 v132, v132, v148
	v_add_f32_e32 v127, v127, v72
	v_fma_f32 v142, v50, s73, -v166
	v_sub_f32_e32 v132, v132, v73
	v_add_f32_e32 v127, v127, v142
	v_fmamk_f32 v142, v50, 0x3f6c835e, v111
	v_sub_f32_e32 v132, v132, v142
	v_add_f32_e32 v127, v127, v178
	v_fma_f32 v142, v48, s72, -v15
	v_sub_f32_e32 v132, v132, v179
	v_add_f32_e32 v127, v127, v142
	v_fmac_f32_e32 v149, 0xbec3ef15, v48
	v_sub_f32_e32 v132, v132, v149
	v_add_f32_e32 v127, v127, v60
	v_fma_f32 v142, v47, s78, -v119
	v_sub_f32_e32 v132, v132, v49
	v_add_f32_e32 v127, v127, v142
	v_fmamk_f32 v142, v47, 0xbec3ef15, v94
	v_sub_f32_e32 v132, v132, v142
	v_add_f32_e32 v127, v127, v180
	v_fma_f32 v142, v46, s79, -v1
	v_sub_f32_e32 v132, v132, v181
	v_add_f32_e32 v127, v127, v142
	v_fmac_f32_e32 v150, 0x3f6c835e, v46
	v_sub_f32_e32 v132, v132, v150
	v_mul_f32_e32 v142, v36, v127
	v_mul_f32_e32 v127, v37, v127
	v_fmac_f32_e32 v142, v37, v132
	v_fma_f32 v127, v36, v132, -v127
	v_mul_f32_e32 v142, 0x3e800000, v142
	v_mul_f32_e32 v127, 0x3e800000, v127
	s_mov_b32 s0, 0x580000
	v_cvt_pk_bf16_f32 v127, v142, v127
	v_add_co_u32_e32 v142, vcc, s0, v12
	v_add_f32_e64 v123, -v54, v123
	s_nop 0
	v_addc_co_u32_e32 v143, vcc, 0, v13, vcc
	global_store_short v[142:143], v127, off
	global_store_short_d16_hi v[142:143], v127, off offset:512
	v_add_f32_e32 v124, v58, v124
	v_sub_f32_e32 v123, v123, v162
	v_fma_f32 v127, v53, 0, -v79
	v_fma_f32 v79, 0, v79, v53
	v_add_f32_e32 v124, v124, v186
	v_sub_f32_e32 v79, v123, v79
	v_add_f32_e32 v124, v124, v127
	v_sub_f32_e32 v79, v79, v59
	v_add_f32_e32 v105, v124, v105
	v_add_f32_e32 v79, v79, v107
	v_add_f32_e32 v105, v105, v110
	v_sub_f32_e32 v79, v79, v116
	v_fma_f32 v74, 0, v74, v51
	v_add_f32_e32 v105, v105, v161
	v_sub_f32_e32 v74, v79, v74
	v_add_f32_e32 v105, v105, v120
	v_sub_f32_e32 v74, v74, v63
	v_fma_f32 v75, v75, 0, -v50
	v_add_f32_e32 v79, v105, v62
	v_sub_f32_e32 v74, v74, v75
	v_add_f32_e32 v79, v79, v106
	v_sub_f32_e32 v74, v74, v121
	v_fma_f32 v76, 0, v76, v48
	v_add_f32_e32 v75, v79, v157
	v_sub_f32_e32 v74, v74, v76
	v_add_f32_e32 v75, v75, v112
	v_sub_f32_e32 v74, v74, v80
	v_fma_f32 v76, v77, 0, -v47
	v_add_f32_e32 v75, v75, v108
	v_sub_f32_e32 v74, v74, v76
	v_add_f32_e32 v75, v75, v109
	v_sub_f32_e32 v74, v74, v115
	v_fma_f32 v76, 0, v78, v46
	v_add_f32_e32 v75, v75, v158
	v_sub_f32_e32 v74, v74, v76
	v_add_f32_e32 v75, v75, v114
	v_mul_f32_e32 v76, v39, v74
	v_fmac_f32_e32 v76, v38, v75
	v_mul_f32_e32 v75, v39, v75
	v_fma_f32 v74, v38, v74, -v75
	v_mul_f32_e32 v76, 0x3e800000, v76
	v_mul_f32_e32 v74, 0x3e800000, v74
	s_mov_b32 s0, 0x600000
	v_cvt_pk_bf16_f32 v76, v76, v74
	v_add_co_u32_e32 v74, vcc, s0, v12
	v_fmac_f32_e32 v83, 0xbf6c835e, v55
	s_nop 0
	v_addc_co_u32_e32 v75, vcc, 0, v13, vcc
	global_store_short v[74:75], v76, off
	global_store_short_d16_hi v[74:75], v76, off offset:512
	v_fma_f32 v74, v55, s73, -v163
	v_add_f32_e32 v74, v58, v74
	v_sub_f32_e64 v75, -v54, v83
	v_add_f32_e32 v74, v74, v125
	v_fma_f32 v76, v53, s72, -v68
	v_sub_f32_e32 v75, v75, v126
	v_add_f32_e32 v74, v74, v76
	v_fmamk_f32 v76, v53, 0x3ec3ef15, v102
	v_sub_f32_e32 v75, v75, v76
	v_add_f32_e32 v74, v74, v82
	v_fma_f32 v76, v52, s78, -v167
	v_sub_f32_e32 v75, v75, v85
	v_add_f32_e32 v74, v74, v76
; __device__ __forceinline__ unsigned cvtpk(float lo, float hi) { unsigned r; asm volatile("v_cvt_pk_bf16_f32 %0, %1, %2" : "=v"(r) : "v"(lo), "v"(hi)); return r; }
; __device__ __forceinline__ float bf2f(unsigned short b) { return __uint_as_float((unsigned)b << 16); }
; __device__ __forceinline__ void fourier_stage_a(const Params& p, const Ctx& c, int l) {
;     ...
;   for (long i = c.gtid; i < (long)NB * 512 * 256; i += c.nthr) { const int t2 = (int)(i & 255), ch = (int)((i >> 8) & 511), b = (int)(i >> 17);
;     const bf16_t* Pb = PT + ((size_t)(0 * NB + b) * 512 + ch) * 4096 + t2; const bf16_t* Qb = PT + ((size_t)(1 * NB + b) * 512 + ch) * 4096 + t2;
;     float zr[16], zq[16];
; #pragma unroll
;     for (int t1 = 0; t1 < 16; ++t1) { zr[t1] = bf2f(Pb[256 * t1]); zq[t1] = bf2f(Qb[256 * t1]); }
;     bf16_t* Yo = Y + ((size_t)(b * 16) * 512 + ch) * 512 + t2;
; #pragma unroll
;     for (int k1 = 0; k1 < 16; ++k1) { float ar = 0.f, ai = 0.f;
; #pragma unroll
;       for (int t1 = 0; t1 < 16; ++t1) { const float cc = C16[(k1 * t1) & 15], ss = S16[(k1 * t1) & 15]; ar += zr[t1] * cc - zq[t1] * ss; ai -= zr[t1] * ss + zq[t1] * cc; }
;       const float ph = (float)(k1 * t2) * (1.f / 4096.f), ct = __builtin_amdgcn_cosf(ph), st = __builtin_amdgcn_sinf(ph);
;       const float yr = (ar * ct + ai * st) * 0.25f, yi = (ai * ct - ar * st) * 0.25f;
;       bf16_t* yo = Yo + (size_t)k1 * 512 * 512; const unsigned w = cvtpk(yr, yi); yo[0] = (bf16_t)(w & 0xffff); yo[256] = (bf16_t)(w >> 16); } }
	v_fmac_f32_e32 v84, 0x3ec3ef15, v52
	v_sub_f32_e32 v75, v75, v84
	v_add_f32_e32 v74, v74, v135
	v_fma_f32 v76, v51, s79, -v71
	v_sub_f32_e32 v75, v75, v86
	v_add_f32_e32 v74, v74, v76
	v_fmamk_f32 v76, v51, 0xbf6c835e, v104
	v_sub_f32_e32 v75, v75, v76
	v_add_f32_e32 v74, v74, v72
	v_fma_f32 v76, v50, s79, -v166
	v_sub_f32_e32 v75, v75, v73
	v_add_f32_e32 v74, v74, v76
	v_fmac_f32_e32 v87, 0x3f6c835e, v50
	v_sub_f32_e32 v75, v75, v87
	v_add_f32_e32 v74, v74, v128
	v_fma_f32 v76, v48, s78, -v15
	v_sub_f32_e32 v75, v75, v129
	v_add_f32_e32 v74, v74, v76
	v_fmamk_f32 v76, v48, 0xbec3ef15, v81
	v_sub_f32_e32 v75, v75, v76
	v_add_f32_e32 v74, v74, v80
	v_fma_f32 v76, v47, s72, -v119
	v_sub_f32_e32 v75, v75, v89
	v_add_f32_e32 v74, v74, v76
	v_fmac_f32_e32 v88, 0xbec3ef15, v47
	v_sub_f32_e32 v75, v75, v88
	v_add_f32_e32 v74, v74, v130
	v_fma_f32 v76, v46, s73, -v1
	v_sub_f32_e32 v75, v75, v90
	v_add_f32_e32 v74, v74, v76
	v_fmamk_f32 v76, v46, 0x3f6c835e, v61
	v_sub_f32_e32 v75, v75, v76
	v_mul_f32_e32 v76, v40, v74
	v_mul_f32_e32 v74, v41, v74
	v_fmac_f32_e32 v76, v41, v75
	v_fma_f32 v74, v40, v75, -v74
	v_mul_f32_e32 v76, 0x3e800000, v76
	v_mul_f32_e32 v74, 0x3e800000, v74
	s_mov_b32 s0, 0x680000
	v_cvt_pk_bf16_f32 v76, v76, v74
	v_add_co_u32_e32 v74, vcc, s0, v12
	v_fmac_f32_e32 v91, 0xbf3504f3, v55
	s_nop 0
	v_addc_co_u32_e32 v75, vcc, 0, v13, vcc
	global_store_short v[74:75], v76, off
	global_store_short_d16_hi v[74:75], v76, off offset:512
	v_fma_f32 v74, v55, s20, -v137
	v_add_f32_e32 v74, v58, v74
	v_sub_f32_e64 v75, -v54, v91
	v_add_f32_e32 v65, v74, v65
	v_sub_f32_e32 v74, v75, v136
	v_fma_f32 v75, v53, s92, -v93
	v_add_f32_e32 v65, v65, v75
	v_fmac_f32_e32 v93, 0xbf3504f3, v53
	v_sub_f32_e32 v74, v74, v93
	v_add_f32_e32 v65, v65, v95
	v_fma_f32 v75, v52, s92, -v140
	v_sub_f32_e32 v74, v74, v82
	v_add_f32_e32 v65, v65, v75
	v_fmac_f32_e32 v92, 0x3f3504f3, v52
	v_sub_f32_e32 v74, v74, v92
	v_add_f32_e32 v65, v65, v116
	v_fma_f32 v75, v51, s20, -v97
	v_sub_f32_e32 v74, v74, v141
	v_add_f32_e32 v65, v65, v75
	v_fmac_f32_e32 v97, 0x3f3504f3, v51
	v_sub_f32_e32 v74, v74, v97
	v_add_f32_e32 v62, v65, v62
	v_fma_f32 v65, v50, s20, -v138
	v_sub_f32_e32 v63, v74, v63
	v_add_f32_e32 v62, v62, v65
	v_fmac_f32_e32 v96, 0xbf3504f3, v50
	v_sub_f32_e32 v63, v63, v96
	v_add_f32_e32 v62, v62, v64
	v_fma_f32 v64, v48, s92, -v98
	v_sub_f32_e32 v63, v63, v131
	v_add_f32_e32 v62, v62, v64
	v_fmac_f32_e32 v98, 0xbf3504f3, v48
	v_sub_f32_e32 v63, v63, v98
	v_add_f32_e32 v62, v62, v100
	v_fma_f32 v64, v47, s92, -v139
	v_sub_f32_e32 v63, v63, v60
	v_add_f32_e32 v62, v62, v64
	v_fmac_f32_e32 v99, 0x3f3504f3, v47
	v_sub_f32_e32 v63, v63, v99
	v_add_f32_e32 v62, v62, v115
	v_fma_f32 v64, v46, s20, -v101
	v_sub_f32_e32 v63, v63, v133
	v_add_f32_e32 v62, v62, v64
	v_fmac_f32_e32 v101, 0x3f3504f3, v46
	v_sub_f32_e32 v63, v63, v101
	v_mul_f32_e32 v64, v42, v62
	v_mul_f32_e32 v62, v43, v62
	v_fmac_f32_e32 v64, v43, v63
	v_fma_f32 v62, v42, v63, -v62
	v_mul_f32_e32 v64, 0x3e800000, v64
	v_mul_f32_e32 v62, 0x3e800000, v62
	s_mov_b32 s0, 0x700000
	v_cvt_pk_bf16_f32 v64, v64, v62
	v_add_co_u32_e32 v62, vcc, s0, v12
	v_fmac_f32_e32 v66, 0xbec3ef15, v55
	s_nop 0
	v_addc_co_u32_e32 v63, vcc, 0, v13, vcc
	global_store_short v[62:63], v64, off
	global_store_short_d16_hi v[62:63], v64, off offset:512
	v_fma_f32 v62, v55, s78, -v117
	v_add_f32_e32 v58, v58, v62
	v_sub_f32_e64 v54, -v54, v66
	v_add_f32_e32 v55, v58, v134
	v_sub_f32_e32 v54, v54, v67
	v_fma_f32 v58, v53, s73, -v102
	v_fmac_f32_e32 v68, 0xbf6c835e, v53
	v_add_f32_e32 v55, v55, v58
	v_sub_f32_e32 v53, v54, v68
	v_add_f32_e32 v54, v55, v59
	v_sub_f32_e32 v53, v53, v103
	v_fma_f32 v55, v52, s79, -v118
	v_fmac_f32_e32 v69, 0xbf6c835e, v52
	v_add_f32_e32 v54, v54, v55
	v_sub_f32_e32 v52, v53, v69
	v_add_f32_e32 v53, v54, v146
	v_sub_f32_e32 v52, v52, v70
	v_fma_f32 v54, v51, s72, -v104
	v_fmac_f32_e32 v71, 0xbec3ef15, v51
	v_add_f32_e32 v53, v53, v54
	v_sub_f32_e32 v51, v52, v71
	v_add_f32_e32 v52, v53, v72
	v_sub_f32_e32 v51, v51, v73
	v_fma_f32 v53, v50, s72, -v111
	v_fmac_f32_e32 v56, 0x3ec3ef15, v50
	v_add_f32_e32 v52, v52, v53
	v_sub_f32_e32 v50, v51, v56
	v_add_f32_e32 v51, v52, v122
	v_sub_f32_e32 v50, v50, v57
	v_fma_f32 v52, v48, s79, -v81
	v_fmac_f32_e32 v15, 0x3f6c835e, v48
	v_add_f32_e32 v51, v51, v52
	v_sub_f32_e32 v15, v50, v15
	v_add_f32_e32 v48, v51, v60
	v_sub_f32_e32 v15, v15, v49
	v_fma_f32 v49, v47, s73, -v94
	v_fmac_f32_e32 v9, 0x3f6c835e, v47
	v_add_f32_e32 v48, v48, v49
	v_sub_f32_e32 v9, v15, v9
	v_add_f32_e32 v15, v48, v113
	v_sub_f32_e32 v9, v9, v14
	v_fma_f32 v14, v46, s78, -v61
	v_add_f32_e32 v14, v15, v14
	v_fmac_f32_e32 v1, 0x3ec3ef15, v46
	v_sub_f32_e32 v1, v9, v1
	v_mul_f32_e32 v9, v44, v14
	v_mul_f32_e32 v14, v45, v14
	v_add_co_u32_e32 v12, vcc, 0x780000, v12
	v_fmac_f32_e32 v9, v45, v1
	v_fma_f32 v1, v44, v1, -v14
	v_addc_co_u32_e32 v13, vcc, 0, v13, vcc
	v_mul_f32_e32 v1, 0x3e800000, v1
	v_cmp_lt_i64_e32 vcc, s[70:71], v[10:11]
	v_mul_f32_e32 v9, 0x3e800000, v9
	v_cvt_pk_bf16_f32 v1, v9, v1
	s_or_b64 s[54:55], vcc, s[54:55]
	global_store_short v[12:13], v1, off
	global_store_short_d16_hi v[12:13], v1, off offset:512
	s_andn2_b64 exec, exec, s[54:55]
	s_cbranch_execnz .LBB0_506
